# attention prologue: removed two dead K-norm gain loads (K is normalised by the pre-pass)
# speedup vs baseline: 1.0131x; 1.0037x over previous
.LBB0_140:
	s_or_b64 exec, exec, s[12:13]
	v_readlane_b32 s2, v254, 24
	s_waitcnt vmcnt(0) lgkmcnt(0)
	s_barrier
	v_mov_b32_e32 v0, s2
	ds_read_b32 v0, v0
	s_mov_b64 s[12:13], -1
	s_waitcnt lgkmcnt(0)
	s_barrier
	v_cmp_le_i32_e32 vcc, s86, v0
	v_readfirstlane_b32 s18, v0
	s_cbranch_vccnz .LBB0_137
	s_cmp_gt_i32 s18, 63
	s_cbranch_scc0 .LBB0_170
	s_sub_i32 s3, s18, 64
	s_lshr_b32 s2, s3, 8
	s_bfe_u32 s11, s3, 0x40004
	v_mov_b32_e32 v40, v222
	s_sub_i32 s2, 7, s2
	s_and_b32 s3, s18, 15
	s_lshl_b32 s36, s11, 11
	s_lshl_b32 s4, s11, 17
	v_readlane_b32 s5, v250, 35
	v_ashrrev_i32_e32 v42, 3, v40
	s_add_u32 s14, s5, s4
	v_readlane_b32 s4, v250, 36
	v_ashrrev_i32_e32 v43, 31, v42
	s_addc_u32 s15, s4, 0
	v_lshl_add_u64 v[0:1], s[36:37], 0, v[42:43]
	v_readlane_b32 s4, v250, 37
	v_lshlrev_b64 v[0:1], 11, v[0:1]
	v_readlane_b32 s5, v250, 38
	v_and_b32_e32 v2, 7, v40
	v_readlane_b32 s16, v254, 30
	v_lshl_add_u64 v[0:1], s[4:5], 0, v[0:1]
	s_lshl_b32 s4, s3, 7
	s_mov_b32 s5, s37
	v_lshl_add_u64 v[0:1], v[0:1], 0, s[4:5]
	s_lshl_b32 s4, s3, 22
	v_readlane_b32 s5, v250, 39
	s_add_u32 s4, s5, s4
	v_readlane_b32 s5, v250, 40
	s_addc_u32 s5, s5, 0
	s_lshl_b32 s11, s11, 12
	s_add_u32 s12, s4, s11
	s_addc_u32 s13, s5, 0
	s_lshl_b32 s4, s3, 8
	v_lshlrev_b32_e32 v96, 4, v2
	v_readlane_b32 s17, v254, 31
	s_add_u32 s4, s16, s4
	v_lshl_add_u64 v[174:175], v[0:1], 0, v[96:97]
	s_addc_u32 s5, s17, 0
	v_lshlrev_b32_e32 v0, 5, v2
	s_lshl_b32 s4, s2, 9
	v_lshlrev_b32_e32 v0, 3, v40
	v_ashrrev_i32_e32 v44, 5, v40
	v_add_u32_e32 v3, 0x200, v40
	s_add_i32 s4, s12, s4
	v_and_b32_e32 v43, 0xf8, v0
	v_ashrrev_i32_e32 v45, 31, v44
	v_ashrrev_i32_e32 v46, 5, v3
	v_lshl_add_u32 v0, v43, 1, s4
	v_lshlrev_b64 v[192:193], 16, v[44:45]
	v_ashrrev_i32_e32 v47, 31, v46
	v_lshl_add_u32 v1, s2, 19, v174
	v_add_u32_e32 v2, v0, v192
	v_lshlrev_b64 v[194:195], 16, v[46:47]
	v_subrev_u32_e32 v1, s74, v1
	v_subrev_u32_e32 v2, s74, v2
	v_add_u32_e32 v3, v0, v194
	v_mov_b32_e32 v106, v1
	v_mov_b32_e32 v110, v2
	v_add_u32_e32 v2, 0x20000, v1
	v_subrev_u32_e32 v3, s74, v3
	v_mov_b32_e32 v114, v2
	v_mov_b32_e32 v118, v3
	v_add_u32_e32 v3, 0x400, v40
	v_ashrrev_i32_e32 v48, 5, v3
	v_ashrrev_i32_e32 v49, 31, v48
	v_lshlrev_b64 v[196:197], 16, v[48:49]
	v_add_u32_e32 v2, 0x40000, v1
	v_add_u32_e32 v3, v0, v196
	v_subrev_u32_e32 v3, s74, v3
	v_mov_b32_e32 v122, v2
	v_mov_b32_e32 v126, v3
	v_add_u32_e32 v2, 0x600, v40
	v_ashrrev_i32_e32 v50, 5, v2
	v_ashrrev_i32_e32 v51, 31, v50
	v_lshlrev_b64 v[198:199], 16, v[50:51]
	v_add_u32_e32 v1, 0x60000, v1
	v_add_u32_e32 v0, v0, v198
	v_subrev_u32_e32 v0, s74, v0
	v_mov_b32_e32 v130, v1
	v_mov_b32_e32 v134, v0
	s_lshl_b32 s5, s3, 13
	s_add_u32 s20, s14, s5
	s_movk_i32 s5, 0x100
	v_cmp_gt_i32_e64 s[42:43], s5, v40
	s_movk_i32 s5, 0xff
	v_readfirstlane_b32 s4, v40
	s_addc_u32 s21, s15, 0
	v_cmp_lt_i32_e32 vcc, s5, v40
	s_and_saveexec_b64 s[14:15], vcc
	s_xor_b64 s[44:45], exec, s[14:15]
	v_mov_b32_e32 v41, v97
	s_or_saveexec_b64 s[44:45], s[44:45]
	s_lshl_b32 s11, s2, 8
	s_lshl_b32 s5, s3, 6
	v_mov_b32_e32 v175, 0
	v_mov_b32_e32 v189, 0
	s_xor_b64 exec, exec, s[44:45]
	s_cbranch_execz .LBB0_146
	s_lshl_b32 s3, s11, 2
	s_add_u32 s14, s20, s3
	s_addc_u32 s15, s21, 0
	v_ashrrev_i32_e32 v41, 31, v40
	v_lshl_add_u64 v[0:1], v[40:41], 2, s[14:15]
	global_load_dword v189, v[0:1], off sc1
